# batched HGRN2 finalize jobs: 18 loads up front, lockstep butterflies, plus static prio for waves 4-7 in MLA loop
# speedup vs baseline: 1.0409x; 1.0177x over previous
; DI int tid_() { int t = threadIdx.x; asm volatile("" : "+v"(t)); return t; }
; DI int bid_() { int b = blockIdx.x; asm volatile("" : "+s"(b)); return b; }
; DI bf16_t f2bf(float x) { return (bf16_t)(pack2(x, 0.f) & 0xffffu); }
; DI float bf2f(bf16_t b) { return __uint_as_float(((unsigned)b) << 16); }
; DI float sigmoidf_(float x) { return 1.f / (1.f + expf(-x)); }
; DI void phase_E(char* smem, const Params& p, int layer) {
;     ...
;   for (int j = (bid_() + G - (J_GLU % G)) % G; j < J_FIN; j += G) {
;     const int w = (tid_() >> 6) & 3, rsel = tid_() >> 8, l = tid_() & 63;
;     const float gn = p.hg_norm_g[layer * 64 + l];
; #pragma unroll
;     for (int rr = 0; rr < 6; ++rr) {
;       const int row = j * 12 + rr * 2 + rsel;
;       const float o = bf2f(p.OF[(size_t)row * 256 + w * 64 + l]) + bf2f(p.OB[(size_t)row * 256 + w * 64 + l]);
;       const float ss = wave_sum(o * o);
;       const float rs = rsqrtf(ss * (1.f / 64.f) + EPSN);
;       const float gt = bf2f(p.PH[(size_t)row * 1280 + 1024 + w * 64 + l]);
;       p.Hn[(size_t)row * DM + 512 + w * 64 + l] = f2bf(o * rs * gn * gt * sigmoidf_(gt));
;     }
;   }
.LBB0_124:
	v_mov_b32_e32 v2, v0
	v_mov_b32_e32 v7, v191
	v_and_b32_e32 v15, 0xc0, v2
	v_mov_b32_e32 v2, v0
	v_lshlrev_b32_e32 v190, 1, v15
	v_ashrrev_i32_e32 v4, 8, v2
	v_mov_b32_e32 v2, v0
	s_add_i32 s3, s3, s2
	v_and_b32_e32 v16, 63, v2
	v_or_b32_e32 v2, s4, v16
	v_ashrrev_i32_e32 v3, 31, v2
	v_lshl_add_u64 v[2:3], v[2:3], 2, s[48:49]
	global_load_dword v14, v[2:3], off
	v_and_b32_e32 v3, 64, v1
	v_add_u32_e32 v2, s5, v4
	v_add_u32_e32 v3, 64, v3
	v_xor_b32_e32 v4, 32, v1
	v_cmp_lt_i32_e32 vcc, v4, v3
	v_add_u32_e32 v10, -10, v2
	v_ashrrev_i32_e32 v11, 31, v10
	v_cndmask_b32_e32 v4, v1, v4, vcc
	v_lshlrev_b32_e32 v17, 2, v4
	v_xor_b32_e32 v4, 16, v1
	v_cmp_lt_i32_e32 vcc, v4, v3
	v_lshlrev_b64 v[8:9], 8, v[10:11]
	v_or3_b32 v8, v8, v16, v15
	v_cndmask_b32_e32 v4, v1, v4, vcc
	v_lshlrev_b32_e32 v18, 2, v4
	v_xor_b32_e32 v4, 8, v1
	v_cmp_lt_i32_e32 vcc, v4, v3
	v_lshlrev_b64 v[8:9], 1, v[8:9]
	v_lshl_add_u64 v[12:13], s[60:61], 0, v[8:9]
	v_cndmask_b32_e32 v4, v1, v4, vcc
	v_lshlrev_b32_e32 v19, 2, v4
	v_xor_b32_e32 v4, 4, v1
	v_cmp_lt_i32_e32 vcc, v4, v3
	v_lshl_add_u64 v[8:9], s[62:63], 0, v[8:9]
	v_lshlrev_b32_e32 v6, 1, v16
	v_cndmask_b32_e32 v4, v1, v4, vcc
	v_lshlrev_b32_e32 v20, 2, v4
	v_xor_b32_e32 v4, 2, v1
	v_cmp_lt_i32_e32 vcc, v4, v3
	s_nop 1
	v_cndmask_b32_e32 v4, v1, v4, vcc
	v_lshlrev_b32_e32 v21, 2, v4
	v_xor_b32_e32 v4, 1, v1
	v_cmp_lt_i32_e32 vcc, v4, v3
	s_nop 1
	v_cndmask_b32_e32 v3, v1, v4, vcc
	v_lshlrev_b32_e32 v22, 2, v3
	v_lshl_add_u64 v[4:5], s[68:69], 0, v[190:191]
	v_lshl_add_u64 v[4:5], v[4:5], 0, v[6:7]
	v_mov_b64_e32 v[30:31], s[74:75]
	v_mad_i64_i32 v[32:33], s[8:9], v10, s12, v[30:31]
	v_lshl_add_u64 v[32:33], v[32:33], 0, v[190:191]
	v_lshl_add_u64 v[32:33], v[32:33], 0, v[6:7]
	v_lshlrev_b64 v[34:35], 11, v[10:11]
	v_lshl_add_u64 v[34:35], v[4:5], 0, v[34:35]
	global_load_ushort v40, v[8:9], off
	global_load_ushort v46, v[12:13], off
	global_load_ushort v41, v[8:9], off offset:1024
	global_load_ushort v47, v[12:13], off offset:1024
	global_load_ushort v42, v[8:9], off offset:2048
	global_load_ushort v48, v[12:13], off offset:2048
	global_load_ushort v43, v[8:9], off offset:3072
	global_load_ushort v49, v[12:13], off offset:3072
	v_add_co_u32_e32 v36, vcc, 0x1000, v8
	s_nop 1
	v_addc_co_u32_e32 v37, vcc, 0, v9, vcc
	v_add_co_u32_e32 v38, vcc, 0x1000, v12
	s_nop 1
	v_addc_co_u32_e32 v39, vcc, 0, v13, vcc
	global_load_ushort v44, v[36:37], off
	global_load_ushort v50, v[38:39], off
	global_load_ushort v45, v[36:37], off offset:1024
	global_load_ushort v51, v[38:39], off offset:1024
	global_load_ushort v52, v[32:33], off offset:2048
	v_add_co_u32_e32 v32, vcc, 0x1400, v32
	s_nop 1
	v_addc_co_u32_e32 v33, vcc, 0, v33, vcc
	global_load_ushort v53, v[32:33], off offset:2048
	v_add_co_u32_e32 v32, vcc, 0x1400, v32
	s_nop 1
	v_addc_co_u32_e32 v33, vcc, 0, v33, vcc
	global_load_ushort v54, v[32:33], off offset:2048
	v_add_co_u32_e32 v32, vcc, 0x1400, v32
	s_nop 1
	v_addc_co_u32_e32 v33, vcc, 0, v33, vcc
	global_load_ushort v55, v[32:33], off offset:2048
	v_add_co_u32_e32 v32, vcc, 0x1400, v32
	s_nop 1
	v_addc_co_u32_e32 v33, vcc, 0, v33, vcc
	global_load_ushort v56, v[32:33], off offset:2048
	v_add_co_u32_e32 v32, vcc, 0x1400, v32
	s_nop 1
	v_addc_co_u32_e32 v33, vcc, 0, v33, vcc
	global_load_ushort v57, v[32:33], off offset:2048
	s_waitcnt vmcnt(0)
	v_lshlrev_b32_e32 v40, 16, v40
	v_lshlrev_b32_e32 v46, 16, v46
	v_add_f32_e32 v40, v40, v46
	v_mul_f32_e32 v58, v40, v40
	v_lshlrev_b32_e32 v41, 16, v41
	v_lshlrev_b32_e32 v47, 16, v47
	v_add_f32_e32 v41, v41, v47
	v_mul_f32_e32 v59, v41, v41
	v_lshlrev_b32_e32 v42, 16, v42
	v_lshlrev_b32_e32 v48, 16, v48
	v_add_f32_e32 v42, v42, v48
	v_mul_f32_e32 v60, v42, v42
	v_lshlrev_b32_e32 v43, 16, v43
	v_lshlrev_b32_e32 v49, 16, v49
	v_add_f32_e32 v43, v43, v49
	v_mul_f32_e32 v61, v43, v43
	v_lshlrev_b32_e32 v44, 16, v44
	v_lshlrev_b32_e32 v50, 16, v50
	v_add_f32_e32 v44, v44, v50
	v_mul_f32_e32 v62, v44, v44
	v_lshlrev_b32_e32 v45, 16, v45
	v_lshlrev_b32_e32 v51, 16, v51
	v_add_f32_e32 v45, v45, v51
	v_mul_f32_e32 v63, v45, v45
	ds_bpermute_b32 v58, v17, v58
	ds_bpermute_b32 v59, v17, v59
	ds_bpermute_b32 v60, v17, v60
	ds_bpermute_b32 v61, v17, v61
	ds_bpermute_b32 v62, v17, v62
	ds_bpermute_b32 v63, v17, v63
	s_waitcnt lgkmcnt(0)
	v_fmac_f32_e32 v58, v40, v40
	v_fmac_f32_e32 v59, v41, v41
	v_fmac_f32_e32 v60, v42, v42
	v_fmac_f32_e32 v61, v43, v43
	v_fmac_f32_e32 v62, v44, v44
	v_fmac_f32_e32 v63, v45, v45
	ds_bpermute_b32 v46, v18, v58
	ds_bpermute_b32 v47, v18, v59
	ds_bpermute_b32 v48, v18, v60
	ds_bpermute_b32 v49, v18, v61
	ds_bpermute_b32 v50, v18, v62
	ds_bpermute_b32 v51, v18, v63
	s_waitcnt lgkmcnt(0)
	v_add_f32_e32 v58, v58, v46
	v_add_f32_e32 v59, v59, v47
	v_add_f32_e32 v60, v60, v48
	v_add_f32_e32 v61, v61, v49
	v_add_f32_e32 v62, v62, v50
	v_add_f32_e32 v63, v63, v51
	ds_bpermute_b32 v46, v19, v58
	ds_bpermute_b32 v47, v19, v59
	ds_bpermute_b32 v48, v19, v60
	ds_bpermute_b32 v49, v19, v61
	ds_bpermute_b32 v50, v19, v62
	ds_bpermute_b32 v51, v19, v63
	s_waitcnt lgkmcnt(0)
	v_add_f32_e32 v58, v58, v46
	v_add_f32_e32 v59, v59, v47
	v_add_f32_e32 v60, v60, v48
	v_add_f32_e32 v61, v61, v49
	v_add_f32_e32 v62, v62, v50
	v_add_f32_e32 v63, v63, v51
	ds_bpermute_b32 v46, v20, v58
	ds_bpermute_b32 v47, v20, v59
	ds_bpermute_b32 v48, v20, v60
	ds_bpermute_b32 v49, v20, v61
	ds_bpermute_b32 v50, v20, v62
	ds_bpermute_b32 v51, v20, v63
	s_waitcnt lgkmcnt(0)
	v_add_f32_e32 v58, v58, v46
	v_add_f32_e32 v59, v59, v47
	v_add_f32_e32 v60, v60, v48
	v_add_f32_e32 v61, v61, v49
	v_add_f32_e32 v62, v62, v50
	v_add_f32_e32 v63, v63, v51
	ds_bpermute_b32 v46, v21, v58
	ds_bpermute_b32 v47, v21, v59
	ds_bpermute_b32 v48, v21, v60
	ds_bpermute_b32 v49, v21, v61
	ds_bpermute_b32 v50, v21, v62
	ds_bpermute_b32 v51, v21, v63
	s_waitcnt lgkmcnt(0)
; DI bf16_t f2bf(float x) { return (bf16_t)(pack2(x, 0.f) & 0xffffu); }
; DI float bf2f(bf16_t b) { return __uint_as_float(((unsigned)b) << 16); }
; DI float sigmoidf_(float x) { return 1.f / (1.f + expf(-x)); }
; DI void phase_E(char* smem, const Params& p, int layer) {
;     ...
;       const float ss = wave_sum(o * o);
;       const float rs = rsqrtf(ss * (1.f / 64.f) + EPSN);
;       const float gt = bf2f(p.PH[(size_t)row * 1280 + 1024 + w * 64 + l]);
;       p.Hn[(size_t)row * DM + 512 + w * 64 + l] = f2bf(o * rs * gn * gt * sigmoidf_(gt));
	v_add_f32_e32 v58, v58, v46
	v_add_f32_e32 v59, v59, v47
	v_add_f32_e32 v60, v60, v48
	v_add_f32_e32 v61, v61, v49
	v_add_f32_e32 v62, v62, v50
	v_add_f32_e32 v63, v63, v51
	ds_bpermute_b32 v46, v22, v58
	ds_bpermute_b32 v47, v22, v59
	ds_bpermute_b32 v48, v22, v60
	ds_bpermute_b32 v49, v22, v61
	ds_bpermute_b32 v50, v22, v62
	ds_bpermute_b32 v51, v22, v63
	s_waitcnt lgkmcnt(0)
	v_add_f32_e32 v58, v58, v46
	v_add_f32_e32 v59, v59, v47
	v_add_f32_e32 v60, v60, v48
	v_add_f32_e32 v61, v61, v49
	v_add_f32_e32 v62, v62, v50
	v_add_f32_e32 v63, v63, v51
	v_fmamk_f32 v58, v58, 0x3c800000, v226
	v_cmp_gt_f32_e32 vcc, s10, v58
	v_mul_f32_e32 v64, 0x4b800000, v58
	s_nop 0
	v_cndmask_b32_e32 v58, v58, v64, vcc
	v_rsq_f32_e32 v58, v58
	s_nop 0
	v_mul_f32_e32 v64, 0x45800000, v58
	v_cndmask_b32_e32 v65, v58, v64, vcc
	v_mul_f32_e32 v40, v40, v65
	v_mul_f32_e32 v40, v14, v40
	v_lshlrev_b32_e32 v52, 16, v52
	v_mul_f32_e32 v64, 0xbfb8aa3b, v52
	v_fma_f32 v65, v52, s11, -v64
	v_rndne_f32_e32 v66, v64
	v_fmac_f32_e32 v65, 0xb2a5705f, v52
	v_sub_f32_e32 v64, v64, v66
	v_add_f32_e32 v64, v64, v65
	v_exp_f32_e32 v64, v64
	v_cvt_i32_f32_e32 v65, v66
	v_cmp_nlt_f32_e32 vcc, s13, v52
	v_mul_f32_e32 v40, v40, v52
	v_ldexp_f32 v64, v64, v65
	v_cndmask_b32_e32 v64, 0, v64, vcc
	v_cmp_ngt_f32_e32 vcc, s14, v52
	s_nop 1
	v_cndmask_b32_e32 v52, v239, v64, vcc
	v_add_f32_e32 v52, 1.0, v52
	v_div_scale_f32 v64, s[8:9], v52, v52, 1.0
	v_rcp_f32_e32 v65, v64
	s_nop 0
	v_fma_f32 v66, -v64, v65, 1.0
	v_fmac_f32_e32 v65, v66, v65
	v_div_scale_f32 v66, vcc, 1.0, v52, 1.0
	v_mul_f32_e32 v67, v66, v65
	v_fma_f32 v68, -v64, v67, v66
	v_fmac_f32_e32 v67, v68, v65
	v_fma_f32 v64, -v64, v67, v66
	v_div_fmas_f32 v64, v64, v65, v67
	v_div_fixup_f32 v52, v64, v52, 1.0
	v_mul_f32_e32 v40, v52, v40
	v_cvt_pk_bf16_f32 v40, v40, s0
	global_store_short v[34:35], v40, off offset:1024
	v_add_co_u32_e32 v34, vcc, 0x1000, v34
	s_nop 1
	v_addc_co_u32_e32 v35, vcc, 0, v35, vcc
	v_fmamk_f32 v59, v59, 0x3c800000, v226
	v_cmp_gt_f32_e32 vcc, s10, v59
	v_mul_f32_e32 v64, 0x4b800000, v59
	s_nop 0
	v_cndmask_b32_e32 v59, v59, v64, vcc
	v_rsq_f32_e32 v59, v59
	s_nop 0
	v_mul_f32_e32 v64, 0x45800000, v59
	v_cndmask_b32_e32 v65, v59, v64, vcc
	v_mul_f32_e32 v41, v41, v65
	v_mul_f32_e32 v41, v14, v41
	v_lshlrev_b32_e32 v53, 16, v53
	v_mul_f32_e32 v64, 0xbfb8aa3b, v53
	v_fma_f32 v65, v53, s11, -v64
	v_rndne_f32_e32 v66, v64
	v_fmac_f32_e32 v65, 0xb2a5705f, v53
	v_sub_f32_e32 v64, v64, v66
	v_add_f32_e32 v64, v64, v65
	v_exp_f32_e32 v64, v64
	v_cvt_i32_f32_e32 v65, v66
	v_cmp_nlt_f32_e32 vcc, s13, v53
	v_mul_f32_e32 v41, v41, v53
	v_ldexp_f32 v64, v64, v65
	v_cndmask_b32_e32 v64, 0, v64, vcc
	v_cmp_ngt_f32_e32 vcc, s14, v53
	s_nop 1
	v_cndmask_b32_e32 v53, v239, v64, vcc
	v_add_f32_e32 v53, 1.0, v53
	v_div_scale_f32 v64, s[8:9], v53, v53, 1.0
	v_rcp_f32_e32 v65, v64
	s_nop 0
	v_fma_f32 v66, -v64, v65, 1.0
	v_fmac_f32_e32 v65, v66, v65
	v_div_scale_f32 v66, vcc, 1.0, v53, 1.0
	v_mul_f32_e32 v67, v66, v65
	v_fma_f32 v68, -v64, v67, v66
	v_fmac_f32_e32 v67, v68, v65
	v_fma_f32 v64, -v64, v67, v66
	v_div_fmas_f32 v64, v64, v65, v67
	v_div_fixup_f32 v53, v64, v53, 1.0
	v_mul_f32_e32 v41, v53, v41
	v_cvt_pk_bf16_f32 v41, v41, s0
	global_store_short v[34:35], v41, off offset:1024
	v_add_co_u32_e32 v34, vcc, 0x1000, v34
	s_nop 1
	v_addc_co_u32_e32 v35, vcc, 0, v35, vcc
	v_fmamk_f32 v60, v60, 0x3c800000, v226
	v_cmp_gt_f32_e32 vcc, s10, v60
	v_mul_f32_e32 v64, 0x4b800000, v60
	s_nop 0
	v_cndmask_b32_e32 v60, v60, v64, vcc
	v_rsq_f32_e32 v60, v60
	s_nop 0
	v_mul_f32_e32 v64, 0x45800000, v60
	v_cndmask_b32_e32 v65, v60, v64, vcc
	v_mul_f32_e32 v42, v42, v65
	v_mul_f32_e32 v42, v14, v42
	v_lshlrev_b32_e32 v54, 16, v54
	v_mul_f32_e32 v64, 0xbfb8aa3b, v54
	v_fma_f32 v65, v54, s11, -v64
	v_rndne_f32_e32 v66, v64
	v_fmac_f32_e32 v65, 0xb2a5705f, v54
	v_sub_f32_e32 v64, v64, v66
	v_add_f32_e32 v64, v64, v65
	v_exp_f32_e32 v64, v64
	v_cvt_i32_f32_e32 v65, v66
	v_cmp_nlt_f32_e32 vcc, s13, v54
	v_mul_f32_e32 v42, v42, v54
	v_ldexp_f32 v64, v64, v65
	v_cndmask_b32_e32 v64, 0, v64, vcc
	v_cmp_ngt_f32_e32 vcc, s14, v54
	s_nop 1
	v_cndmask_b32_e32 v54, v239, v64, vcc
	v_add_f32_e32 v54, 1.0, v54
	v_div_scale_f32 v64, s[8:9], v54, v54, 1.0
	v_rcp_f32_e32 v65, v64
	s_nop 0
	v_fma_f32 v66, -v64, v65, 1.0
	v_fmac_f32_e32 v65, v66, v65
	v_div_scale_f32 v66, vcc, 1.0, v54, 1.0
	v_mul_f32_e32 v67, v66, v65
	v_fma_f32 v68, -v64, v67, v66
	v_fmac_f32_e32 v67, v68, v65
	v_fma_f32 v64, -v64, v67, v66
; DI bf16_t f2bf(float x) { return (bf16_t)(pack2(x, 0.f) & 0xffffu); }
; DI float bf2f(bf16_t b) { return __uint_as_float(((unsigned)b) << 16); }
; DI float sigmoidf_(float x) { return 1.f / (1.f + expf(-x)); }
; DI void phase_E(char* smem, const Params& p, int layer) {
;     ...
;       const float ss = wave_sum(o * o);
;       const float rs = rsqrtf(ss * (1.f / 64.f) + EPSN);
;       const float gt = bf2f(p.PH[(size_t)row * 1280 + 1024 + w * 64 + l]);
;       p.Hn[(size_t)row * DM + 512 + w * 64 + l] = f2bf(o * rs * gn * gt * sigmoidf_(gt));
	v_div_fmas_f32 v64, v64, v65, v67
	v_div_fixup_f32 v54, v64, v54, 1.0
	v_mul_f32_e32 v42, v54, v42
	v_cvt_pk_bf16_f32 v42, v42, s0
	global_store_short v[34:35], v42, off offset:1024
	v_add_co_u32_e32 v34, vcc, 0x1000, v34
	s_nop 1
	v_addc_co_u32_e32 v35, vcc, 0, v35, vcc
	v_fmamk_f32 v61, v61, 0x3c800000, v226
	v_cmp_gt_f32_e32 vcc, s10, v61
	v_mul_f32_e32 v64, 0x4b800000, v61
	s_nop 0
	v_cndmask_b32_e32 v61, v61, v64, vcc
	v_rsq_f32_e32 v61, v61
	s_nop 0
	v_mul_f32_e32 v64, 0x45800000, v61
	v_cndmask_b32_e32 v65, v61, v64, vcc
	v_mul_f32_e32 v43, v43, v65
	v_mul_f32_e32 v43, v14, v43
	v_lshlrev_b32_e32 v55, 16, v55
	v_mul_f32_e32 v64, 0xbfb8aa3b, v55
	v_fma_f32 v65, v55, s11, -v64
	v_rndne_f32_e32 v66, v64
	v_fmac_f32_e32 v65, 0xb2a5705f, v55
	v_sub_f32_e32 v64, v64, v66
	v_add_f32_e32 v64, v64, v65
	v_exp_f32_e32 v64, v64
	v_cvt_i32_f32_e32 v65, v66
	v_cmp_nlt_f32_e32 vcc, s13, v55
	v_mul_f32_e32 v43, v43, v55
	v_ldexp_f32 v64, v64, v65
	v_cndmask_b32_e32 v64, 0, v64, vcc
	v_cmp_ngt_f32_e32 vcc, s14, v55
	s_nop 1
	v_cndmask_b32_e32 v55, v239, v64, vcc
	v_add_f32_e32 v55, 1.0, v55
	v_div_scale_f32 v64, s[8:9], v55, v55, 1.0
	v_rcp_f32_e32 v65, v64
	s_nop 0
	v_fma_f32 v66, -v64, v65, 1.0
	v_fmac_f32_e32 v65, v66, v65
	v_div_scale_f32 v66, vcc, 1.0, v55, 1.0
	v_mul_f32_e32 v67, v66, v65
	v_fma_f32 v68, -v64, v67, v66
	v_fmac_f32_e32 v67, v68, v65
	v_fma_f32 v64, -v64, v67, v66
	v_div_fmas_f32 v64, v64, v65, v67
	v_div_fixup_f32 v55, v64, v55, 1.0
	v_mul_f32_e32 v43, v55, v43
	v_cvt_pk_bf16_f32 v43, v43, s0
	global_store_short v[34:35], v43, off offset:1024
	v_add_co_u32_e32 v34, vcc, 0x1000, v34
	s_nop 1
	v_addc_co_u32_e32 v35, vcc, 0, v35, vcc
	v_fmamk_f32 v62, v62, 0x3c800000, v226
	v_cmp_gt_f32_e32 vcc, s10, v62
	v_mul_f32_e32 v64, 0x4b800000, v62
	s_nop 0
	v_cndmask_b32_e32 v62, v62, v64, vcc
	v_rsq_f32_e32 v62, v62
	s_nop 0
	v_mul_f32_e32 v64, 0x45800000, v62
	v_cndmask_b32_e32 v65, v62, v64, vcc
	v_mul_f32_e32 v44, v44, v65
	v_mul_f32_e32 v44, v14, v44
	v_lshlrev_b32_e32 v56, 16, v56
	v_mul_f32_e32 v64, 0xbfb8aa3b, v56
	v_fma_f32 v65, v56, s11, -v64
	v_rndne_f32_e32 v66, v64
	v_fmac_f32_e32 v65, 0xb2a5705f, v56
	v_sub_f32_e32 v64, v64, v66
	v_add_f32_e32 v64, v64, v65
	v_exp_f32_e32 v64, v64
	v_cvt_i32_f32_e32 v65, v66
	v_cmp_nlt_f32_e32 vcc, s13, v56
	v_mul_f32_e32 v44, v44, v56
	v_ldexp_f32 v64, v64, v65
	v_cndmask_b32_e32 v64, 0, v64, vcc
	v_cmp_ngt_f32_e32 vcc, s14, v56
	s_nop 1
	v_cndmask_b32_e32 v56, v239, v64, vcc
	v_add_f32_e32 v56, 1.0, v56
	v_div_scale_f32 v64, s[8:9], v56, v56, 1.0
	v_rcp_f32_e32 v65, v64
	s_nop 0
	v_fma_f32 v66, -v64, v65, 1.0
	v_fmac_f32_e32 v65, v66, v65
	v_div_scale_f32 v66, vcc, 1.0, v56, 1.0
	v_mul_f32_e32 v67, v66, v65
	v_fma_f32 v68, -v64, v67, v66
	v_fmac_f32_e32 v67, v68, v65
	v_fma_f32 v64, -v64, v67, v66
	v_div_fmas_f32 v64, v64, v65, v67
	v_div_fixup_f32 v56, v64, v56, 1.0
	v_mul_f32_e32 v44, v56, v44
	v_cvt_pk_bf16_f32 v44, v44, s0
	global_store_short v[34:35], v44, off offset:1024
	v_add_co_u32_e32 v34, vcc, 0x1000, v34
	s_nop 1
	v_addc_co_u32_e32 v35, vcc, 0, v35, vcc
	v_fmamk_f32 v63, v63, 0x3c800000, v226
	v_cmp_gt_f32_e32 vcc, s10, v63
	v_mul_f32_e32 v64, 0x4b800000, v63
	s_nop 0
	v_cndmask_b32_e32 v63, v63, v64, vcc
	v_rsq_f32_e32 v63, v63
	s_nop 0
	v_mul_f32_e32 v64, 0x45800000, v63
	v_cndmask_b32_e32 v65, v63, v64, vcc
	v_mul_f32_e32 v45, v45, v65
	v_mul_f32_e32 v45, v14, v45
	v_lshlrev_b32_e32 v57, 16, v57
	v_mul_f32_e32 v64, 0xbfb8aa3b, v57
	v_fma_f32 v65, v57, s11, -v64
	v_rndne_f32_e32 v66, v64
	v_fmac_f32_e32 v65, 0xb2a5705f, v57
	v_sub_f32_e32 v64, v64, v66
	v_add_f32_e32 v64, v64, v65
	v_exp_f32_e32 v64, v64
	v_cvt_i32_f32_e32 v65, v66
	v_cmp_nlt_f32_e32 vcc, s13, v57
	v_mul_f32_e32 v45, v45, v57
	v_ldexp_f32 v64, v64, v65
	v_cndmask_b32_e32 v64, 0, v64, vcc
	v_cmp_ngt_f32_e32 vcc, s14, v57
	s_nop 1
	v_cndmask_b32_e32 v57, v239, v64, vcc
	v_add_f32_e32 v57, 1.0, v57
	v_div_scale_f32 v64, s[8:9], v57, v57, 1.0
	v_rcp_f32_e32 v65, v64
	s_nop 0
	v_fma_f32 v66, -v64, v65, 1.0
	v_fmac_f32_e32 v65, v66, v65
	v_div_scale_f32 v66, vcc, 1.0, v57, 1.0
	v_mul_f32_e32 v67, v66, v65
	v_fma_f32 v68, -v64, v67, v66
	v_fmac_f32_e32 v67, v68, v65
	v_fma_f32 v64, -v64, v67, v66
	v_div_fmas_f32 v64, v64, v65, v67
	v_div_fixup_f32 v57, v64, v57, 1.0
	v_mul_f32_e32 v45, v57, v45
	v_cvt_pk_bf16_f32 v45, v45, s0
	global_store_short v[34:35], v45, off offset:1024
	s_mul_i32 s8, s2, 12
	s_add_i32 s5, s5, s8
	s_cmpk_gt_i32 s3, 0xaff
	s_cbranch_scc0 .LBB0_124

; DI unsigned pack2(float a, float b) { hwf2_t f = {a, b}; return __builtin_bit_cast(unsigned, __builtin_convertvector(f, hwbf2_t)); }
; template <int DQK>
; DI void attn_item2(char* smem, const bf16_t* __restrict__ Q, const bf16_t* __restrict__ K, const bf16_t* __restrict__ VT,
;                    int qh, int kvh, int b, int q0, bf16_t* __restrict__ Y, int ycol) {
;     ...
; #pragma unroll
;   for (int qn = 0; qn < 2; ++qn) {
;     const float lt = lsum[qn] + __shfl_xor(lsum[qn], 32, 64);
;     const float inv = 1.f / lt;
;     bf16_t* yp = Y + ((size_t)b * TT + q0 + w * 64 + qn * 32 + r) * DM + ycol;
; #pragma unroll
;     for (int g = 0; g < 4; ++g) {
;       uint2 u0, u1;
;       u0.x = pack2(o[qn][0][4 * g] * inv, o[qn][0][4 * g + 1] * inv); u0.y = pack2(o[qn][0][4 * g + 2] * inv, o[qn][0][4 * g + 3] * inv);
;       u1.x = pack2(o[qn][1][4 * g] * inv, o[qn][1][4 * g + 1] * inv); u1.y = pack2(o[qn][1][4 * g + 2] * inv, o[qn][1][4 * g + 3] * inv);
;       *(uint2*)(yp + 8 * g + 4 * h) = u0;
;       *(uint2*)(yp + 32 + 8 * g + 4 * h) = u1;
;     }
;   }
.LBB0_141:
	s_setprio 0
	v_and_b32_e32 v67, 64, v1
	v_xor_b32_e32 v66, 32, v1
	v_add_u32_e32 v67, 64, v67
	v_cmp_lt_i32_e32 vcc, v66, v67
	s_ashr_i32 s2, s6, 2
	v_mov_b32_e32 v231, 0x2100
	v_cndmask_b32_e32 v66, v1, v66, vcc
	v_lshlrev_b32_e32 v69, 2, v66
	ds_bpermute_b32 v68, v69, v215
	v_mad_i64_i32 v[66:67], s[2:3], s2, v231, v[198:199]
	s_and_b32 s5, s5, 0xc0
	v_readlane_b32 s52, v253, 40
	s_waitcnt lgkmcnt(0)
	v_add_f32_e32 v68, v215, v68
	v_div_scale_f32 v70, s[2:3], v68, v68, 1.0
	v_rcp_f32_e32 v71, v70
	s_lshl_b32 s2, s5, 1
	v_or_b32_e32 v66, v66, v240
	v_readlane_b32 s53, v253, 41
	v_fma_f32 v72, -v70, v71, 1.0
	v_fmac_f32_e32 v71, v72, v71
	v_div_scale_f32 v72, vcc, 1.0, v68, 1.0
	v_mul_f32_e32 v73, v72, v71
	v_fma_f32 v74, -v70, v73, v72
	v_fmac_f32_e32 v73, v74, v71
	v_fma_f32 v70, -v70, v73, v72
	v_div_fmas_f32 v70, v70, v71, v73
	s_add_u32 s2, s52, s2
	v_div_fixup_f32 v68, v70, v68, 1.0
	s_addc_u32 s3, s53, 0
	v_lshlrev_b64 v[66:67], 11, v[66:67]
	v_pk_mul_f32 v[34:35], v[34:35], v[68:69] op_sel_hi:[1,0]
	v_pk_mul_f32 v[36:37], v[36:37], v[68:69] op_sel_hi:[1,0]
	v_lshl_add_u64 v[66:67], s[2:3], 0, v[66:67]
	v_cvt_pk_bf16_f32 v34, v34, v35
	v_cvt_pk_bf16_f32 v35, v36, v37
	v_pk_mul_f32 v[36:37], v[50:51], v[68:69] op_sel_hi:[1,0]
	v_pk_mul_f32 v[50:51], v[52:53], v[68:69] op_sel_hi:[1,0]
	v_lshl_add_u64 v[66:67], v[66:67], 0, v[190:191]
	v_cvt_pk_bf16_f32 v36, v36, v37
	v_cvt_pk_bf16_f32 v37, v50, v51
	global_store_dwordx2 v[66:67], v[34:35], off offset:1536
	global_store_dwordx2 v[66:67], v[36:37], off offset:1600
	v_pk_mul_f32 v[36:37], v[40:41], v[68:69] op_sel_hi:[1,0]
	ds_bpermute_b32 v40, v69, v214
	v_pk_mul_f32 v[34:35], v[38:39], v[68:69] op_sel_hi:[1,0]
	v_pk_mul_f32 v[38:39], v[56:57], v[68:69] op_sel_hi:[1,0]
	v_cvt_pk_bf16_f32 v34, v34, v35
	v_cvt_pk_bf16_f32 v35, v36, v37
	v_pk_mul_f32 v[36:37], v[54:55], v[68:69] op_sel_hi:[1,0]
	s_waitcnt lgkmcnt(0)
	v_add_f32_e32 v40, v214, v40
	v_cvt_pk_bf16_f32 v36, v36, v37
	v_cvt_pk_bf16_f32 v37, v38, v39
	global_store_dwordx2 v[66:67], v[34:35], off offset:1552
	global_store_dwordx2 v[66:67], v[36:37], off offset:1616
	v_pk_mul_f32 v[34:35], v[42:43], v[68:69] op_sel_hi:[1,0]
	v_pk_mul_f32 v[36:37], v[44:45], v[68:69] op_sel_hi:[1,0]
	v_div_scale_f32 v41, s[2:3], v40, v40, 1.0
	v_cvt_pk_bf16_f32 v34, v34, v35
	v_cvt_pk_bf16_f32 v35, v36, v37
	v_pk_mul_f32 v[36:37], v[58:59], v[68:69] op_sel_hi:[1,0]
	v_pk_mul_f32 v[38:39], v[60:61], v[68:69] op_sel_hi:[1,0]
	v_rcp_f32_e32 v42, v41
	v_cvt_pk_bf16_f32 v36, v36, v37
	v_cvt_pk_bf16_f32 v37, v38, v39
	global_store_dwordx2 v[66:67], v[34:35], off offset:1568
	global_store_dwordx2 v[66:67], v[36:37], off offset:1632
	v_pk_mul_f32 v[34:35], v[46:47], v[68:69] op_sel_hi:[1,0]
	v_pk_mul_f32 v[36:37], v[48:49], v[68:69] op_sel_hi:[1,0]
	v_cvt_pk_bf16_f32 v34, v34, v35
	v_cvt_pk_bf16_f32 v35, v36, v37
	v_pk_mul_f32 v[36:37], v[62:63], v[68:69] op_sel_hi:[1,0]
	v_pk_mul_f32 v[38:39], v[64:65], v[68:69] op_sel_hi:[1,0]
	v_cvt_pk_bf16_f32 v36, v36, v37
	v_cvt_pk_bf16_f32 v37, v38, v39
	global_store_dwordx2 v[66:67], v[34:35], off offset:1584
	global_store_dwordx2 v[66:67], v[36:37], off offset:1648
	v_fma_f32 v34, -v41, v42, 1.0
	v_fmac_f32_e32 v42, v34, v42
	v_div_scale_f32 v34, vcc, 1.0, v40, 1.0
	v_mul_f32_e32 v35, v34, v42
	v_fma_f32 v36, -v41, v35, v34
	v_fmac_f32_e32 v35, v36, v42
	v_fma_f32 v34, -v41, v35, v34
	v_div_fmas_f32 v34, v34, v42, v35
	v_div_fixup_f32 v38, v34, v40, 1.0
	s_mov_b64 s[2:3], 0x10600
	v_lshl_add_u64 v[36:37], v[66:67], 0, s[2:3]
	s_mov_b64 s[2:3], 0x10640
	v_pk_mul_f32 v[2:3], v[2:3], v[38:39] op_sel_hi:[1,0]
	v_pk_mul_f32 v[4:5], v[4:5], v[38:39] op_sel_hi:[1,0]
	v_lshl_add_u64 v[34:35], v[66:67], 0, s[2:3]
	v_cvt_pk_bf16_f32 v2, v2, v3
	v_cvt_pk_bf16_f32 v3, v4, v5
	v_pk_mul_f32 v[4:5], v[18:19], v[38:39] op_sel_hi:[1,0]
	v_pk_mul_f32 v[18:19], v[20:21], v[38:39] op_sel_hi:[1,0]
	s_mov_b32 s2, 0x10000
	v_cvt_pk_bf16_f32 v4, v4, v5
	v_cvt_pk_bf16_f32 v5, v18, v19
	v_add_co_u32_e32 v18, vcc, s2, v66
	v_readlane_b32 s54, v253, 42
	s_nop 0
	v_addc_co_u32_e32 v19, vcc, 0, v67, vcc
	global_store_dwordx2 v[18:19], v[2:3], off offset:1536
	global_store_dwordx2 v[18:19], v[4:5], off offset:1600
	v_pk_mul_f32 v[2:3], v[6:7], v[38:39] op_sel_hi:[1,0]
	v_pk_mul_f32 v[4:5], v[8:9], v[38:39] op_sel_hi:[1,0]
	v_cvt_pk_bf16_f32 v2, v2, v3
	v_cvt_pk_bf16_f32 v3, v4, v5
	v_pk_mul_f32 v[4:5], v[22:23], v[38:39] op_sel_hi:[1,0]
	v_pk_mul_f32 v[6:7], v[24:25], v[38:39] op_sel_hi:[1,0]
	v_cvt_pk_bf16_f32 v4, v4, v5
	v_cvt_pk_bf16_f32 v5, v6, v7
	global_store_dwordx2 v[36:37], v[2:3], off offset:16
	global_store_dwordx2 v[34:35], v[4:5], off offset:16
	v_pk_mul_f32 v[2:3], v[10:11], v[38:39] op_sel_hi:[1,0]
	v_pk_mul_f32 v[4:5], v[12:13], v[38:39] op_sel_hi:[1,0]
	v_cvt_pk_bf16_f32 v2, v2, v3
	v_cvt_pk_bf16_f32 v3, v4, v5
	v_pk_mul_f32 v[4:5], v[26:27], v[38:39] op_sel_hi:[1,0]
	v_pk_mul_f32 v[6:7], v[28:29], v[38:39] op_sel_hi:[1,0]
	v_cvt_pk_bf16_f32 v4, v4, v5
	v_cvt_pk_bf16_f32 v5, v6, v7
	v_readlane_b32 s55, v253, 43
	v_readlane_b32 s56, v253, 44
	v_readlane_b32 s57, v253, 45
	v_readlane_b32 s58, v253, 46
	v_readlane_b32 s59, v253, 47
	v_readlane_b32 s60, v253, 48
	v_readlane_b32 s61, v253, 49
	v_readlane_b32 s62, v253, 50
	v_readlane_b32 s63, v253, 51
	v_readlane_b32 s64, v253, 52
	v_readlane_b32 s65, v253, 53
	v_readlane_b32 s66, v253, 54
	v_readlane_b32 s67, v253, 55
	global_store_dwordx2 v[36:37], v[2:3], off offset:32
	global_store_dwordx2 v[34:35], v[4:5], off offset:32
	v_pk_mul_f32 v[2:3], v[14:15], v[38:39] op_sel_hi:[1,0]
	v_pk_mul_f32 v[4:5], v[16:17], v[38:39] op_sel_hi:[1,0]
	v_pk_mul_f32 v[6:7], v[30:31], v[38:39] op_sel_hi:[1,0]
	v_pk_mul_f32 v[8:9], v[32:33], v[38:39] op_sel_hi:[1,0]
	v_mov_b32_e32 v226, 0x358637bd
	v_mov_b32_e32 v227, v197
	v_mov_b32_e32 v197, v195
	v_mov_b32_e32 v195, 0x3bf
	v_mov_b32_e32 v233, v194
	v_mov_b32_e32 v194, 0xb9500d01
	v_mov_b32_e32 v234, v196
	v_mov_b32_e32 v196, 0x37d00d01
	v_mov_b32_e32 v235, 0x8ff
	v_mov_b32_e32 v236, 0x93f
	v_mov_b32_e32 v237, 0x97f
	v_mov_b32_e32 v238, 0x118
	v_mov_b32_e32 v240, 0x110
	v_mov_b32_e32 v241, 0x42800000
	v_not_b32_e32 v242, 63

; #define MFMA32(a, b, c) __builtin_amdgcn_mfma_f32_32x32x16_bf16((a), (b), (c), 0, 0, 0)
; DI unsigned pack2(float a, float b) { hwf2_t f = {a, b}; return __builtin_bit_cast(unsigned, __builtin_convertvector(f, hwbf2_t)); }
; template <int DQK>
; DI void attn_item2(char* smem, const bf16_t* __restrict__ Q, const bf16_t* __restrict__ K, const bf16_t* __restrict__ VT,
;                    int qh, int kvh, int b, int q0, bf16_t* __restrict__ Y, int ycol) {
;     ...
; #pragma unroll
;     for (int mt = 0; mt < 2; ++mt) {
; #pragma unroll
;       for (int qn = 0; qn < 2; ++qn) {
;         float rsum = 0;
; #pragma unroll
;         for (int i = 0; i < 16; ++i) { s[qn][mt][i] = __builtin_amdgcn_exp2f(s[qn][mt][i]); rsum += s[qn][mt][i]; }
;         lsum[qn] += rsum;
;       }
; #pragma unroll
;       for (int sx = 0; sx < 2; ++sx) {
;         const int base = mt * 32 + sx * 16 + 4 * h;
;         union { bf16x8 v; uint2 u[2]; } va, vb;
;         va.u[0] = *(const uint2*)(sV + r * VSTR + base);
;         va.u[1] = *(const uint2*)(sV + r * VSTR + base + 8);
;         vb.u[0] = *(const uint2*)(sV + (32 + r) * VSTR + base);
;         vb.u[1] = *(const uint2*)(sV + (32 + r) * VSTR + base + 8);
; #pragma unroll
;         for (int qn = 0; qn < 2; ++qn) {
;           union { bf16x8 v; unsigned u[4]; } pk;
;           pk.u[0] = pack2(s[qn][mt][8 * sx + 0], s[qn][mt][8 * sx + 1]); pk.u[1] = pack2(s[qn][mt][8 * sx + 2], s[qn][mt][8 * sx + 3]);
;           pk.u[2] = pack2(s[qn][mt][8 * sx + 4], s[qn][mt][8 * sx + 5]); pk.u[3] = pack2(s[qn][mt][8 * sx + 6], s[qn][mt][8 * sx + 7]);
;           o[qn][0] = MFMA32(va.v, pk.v, o[qn][0]);
;           o[qn][1] = MFMA32(vb.v, pk.v, o[qn][1]);
;         }
;       }
;     }
.LBB0_158:
	v_lshlrev_b32_e32 v190, 3, v46
	v_mul_u32_u24_e32 v237, 0x90, v240
	v_exp_f32_e32 v120, v6
	v_add3_u32 v6, 0, v237, v190
	v_add_u32_e32 v192, 0x3000, v6
	v_add_u32_e32 v193, 0x4000, v6
	v_exp_f32_e32 v129, v18
	v_exp_f32_e32 v127, v19
	v_exp_f32_e32 v125, v20
	v_exp_f32_e32 v123, v21
	v_exp_f32_e32 v128, v2
	v_exp_f32_e32 v126, v3
	v_exp_f32_e32 v124, v4
	v_exp_f32_e32 v122, v5
	ds_read2_b64 v[2:5], v192 offset0:128 offset1:130
	ds_read2_b64 v[214:217], v192 offset0:132 offset1:134
	ds_read2_b64 v[18:21], v193 offset0:192 offset1:194
	v_exp_f32_e32 v121, v22
	v_exp_f32_e32 v119, v23
	v_exp_f32_e32 v117, v24
	v_exp_f32_e32 v115, v25
	v_exp_f32_e32 v118, v7
	v_exp_f32_e32 v116, v8
	v_exp_f32_e32 v114, v9
	v_cvt_pk_bf16_f32 v6, v129, v127
	v_cvt_pk_bf16_f32 v7, v125, v123
	v_cvt_pk_bf16_f32 v8, v121, v119
	v_cvt_pk_bf16_f32 v9, v117, v115
	ds_read2_b64 v[218:221], v193 offset0:196 offset1:198
	v_lshlrev_b32_e32 v238, 2, v46
	s_waitcnt lgkmcnt(3)
	v_mfma_f32_32x32x16_bf16 v[34:49], v[2:5], v[6:9], 0
	v_cvt_pk_bf16_f32 v22, v128, v126
	v_cvt_pk_bf16_f32 v23, v124, v122
	v_cvt_pk_bf16_f32 v24, v120, v118
	v_cvt_pk_bf16_f32 v25, v116, v114
	v_exp_f32_e32 v112, v10
	v_exp_f32_e32 v110, v11
	v_exp_f32_e32 v108, v12
	s_waitcnt lgkmcnt(1)
	v_mfma_f32_32x32x16_bf16 v[50:65], v[18:21], v[6:9], 0
	v_exp_f32_e32 v106, v13
	v_exp_f32_e32 v104, v14
	v_exp_f32_e32 v102, v15
	v_exp_f32_e32 v100, v16
	v_exp_f32_e32 v98, v17
	v_exp_f32_e32 v113, v26
	v_exp_f32_e32 v111, v27
	v_mfma_f32_32x32x16_bf16 v[2:17], v[2:5], v[22:25], 0
	v_exp_f32_e32 v109, v28
	v_exp_f32_e32 v107, v29
	v_exp_f32_e32 v105, v30
	v_exp_f32_e32 v103, v31
	v_exp_f32_e32 v101, v32
	v_exp_f32_e32 v99, v33
	v_cvt_pk_bf16_f32 v222, v113, v111
	v_mfma_f32_32x32x16_bf16 v[18:33], v[18:21], v[22:25], 0
	v_cvt_pk_bf16_f32 v223, v109, v107
	v_cvt_pk_bf16_f32 v224, v105, v103
	v_cvt_pk_bf16_f32 v225, v101, v99
	v_exp_f32_e32 v235, v82
	v_exp_f32_e32 v233, v83
	v_exp_f32_e32 v231, v84
	v_exp_f32_e32 v229, v85
	v_mfma_f32_32x32x16_bf16 v[34:49], v[214:217], v[222:225], v[34:49]
	v_exp_f32_e32 v227, v86
	v_exp_f32_e32 v234, v66
	v_exp_f32_e32 v232, v67
	v_exp_f32_e32 v230, v68
	v_exp_f32_e32 v228, v69
	v_exp_f32_e32 v226, v70
	v_exp_f32_e32 v85, v96
	s_waitcnt lgkmcnt(0)
	v_mfma_f32_32x32x16_bf16 v[50:65], v[218:221], v[222:225], v[50:65]
	v_cvt_pk_bf16_f32 v222, v112, v110
	v_cvt_pk_bf16_f32 v223, v108, v106
	v_cvt_pk_bf16_f32 v224, v104, v102
	v_cvt_pk_bf16_f32 v225, v100, v98
	v_exp_f32_e32 v83, v97
	v_exp_f32_e32 v86, v79
	v_exp_f32_e32 v84, v80
	v_mfma_f32_32x32x16_bf16 v[2:17], v[214:217], v[222:225], v[2:17]
	v_exp_f32_e32 v216, v75
	v_exp_f32_e32 v214, v76
	v_cvt_pk_bf16_f32 v75, v231, v229
	v_exp_f32_e32 v217, v91
	v_exp_f32_e32 v215, v92
	v_exp_f32_e32 v91, v93
	v_exp_f32_e32 v82, v81
	v_mfma_f32_32x32x16_bf16 v[18:33], v[218:221], v[222:225], v[18:33]
	v_exp_f32_e32 v225, v87
	v_exp_f32_e32 v223, v88
	v_exp_f32_e32 v221, v89
	v_exp_f32_e32 v224, v71
	v_exp_f32_e32 v222, v72
	v_exp_f32_e32 v220, v73
	ds_read2_b64 v[66:69], v192 offset0:136 offset1:138
	ds_read2_b64 v[70:73], v193 offset0:200 offset1:202
	v_exp_f32_e32 v219, v90
	v_exp_f32_e32 v218, v74
	v_exp_f32_e32 v90, v77
	v_cvt_pk_bf16_f32 v74, v235, v233
	v_cvt_pk_bf16_f32 v76, v227, v225
	v_cvt_pk_bf16_f32 v77, v223, v221
	v_exp_f32_e32 v89, v94
	v_exp_f32_e32 v87, v95
	s_waitcnt lgkmcnt(1)
	v_mfma_f32_32x32x16_bf16 v[34:49], v[66:69], v[74:77], v[34:49]
	v_exp_f32_e32 v88, v78
	s_mov_b32 s2, 2
	s_waitcnt lgkmcnt(0)
	v_mfma_f32_32x32x16_bf16 v[50:65], v[70:73], v[74:77], v[50:65]
	v_cvt_pk_bf16_f32 v74, v234, v232
	v_cvt_pk_bf16_f32 v75, v230, v228
	v_cvt_pk_bf16_f32 v76, v226, v224
	v_cvt_pk_bf16_f32 v77, v222, v220
	s_nop 1
	v_mfma_f32_32x32x16_bf16 v[2:17], v[66:69], v[74:77], v[2:17]
	v_mfma_f32_32x32x16_bf16 v[18:33], v[70:73], v[74:77], v[18:33]
	ds_read2_b64 v[66:69], v192 offset0:140 offset1:142
	ds_read2_b64 v[70:73], v193 offset0:204 offset1:206
	v_cvt_pk_bf16_f32 v74, v219, v217
	v_cvt_pk_bf16_f32 v75, v215, v91
	v_cvt_pk_bf16_f32 v76, v89, v87
	v_cvt_pk_bf16_f32 v77, v85, v83
	s_waitcnt lgkmcnt(1)
	s_nop 0
	v_mfma_f32_32x32x16_bf16 v[34:49], v[66:69], v[74:77], v[34:49]
	s_waitcnt lgkmcnt(0)
	v_mfma_f32_32x32x16_bf16 v[50:65], v[70:73], v[74:77], v[50:65]
	v_cvt_pk_bf16_f32 v74, v218, v216
	v_cvt_pk_bf16_f32 v75, v214, v90
	v_cvt_pk_bf16_f32 v76, v88, v86
	v_cvt_pk_bf16_f32 v77, v84, v82
	s_nop 1
	v_mfma_f32_32x32x16_bf16 v[2:17], v[66:69], v[74:77], v[2:17]
	v_add_f32_e64 v68, v128, 0
	v_add_f32_e64 v69, v129, 0
	v_add_f32_e64 v66, v234, 0
	v_add_f32_e64 v67, v235, 0
	v_add_f32_e64 v68, v126, v68
	v_add_f32_e64 v69, v127, v69
	v_pk_add_f32 v[66:67], v[232:233], v[66:67]
	v_pk_add_f32 v[68:69], v[124:125], v[68:69]
	v_pk_add_f32 v[66:67], v[230:231], v[66:67]
	v_pk_add_f32 v[68:69], v[122:123], v[68:69]
	v_pk_add_f32 v[66:67], v[228:229], v[66:67]
	v_pk_add_f32 v[68:69], v[120:121], v[68:69]
	v_pk_add_f32 v[66:67], v[226:227], v[66:67]
	v_pk_add_f32 v[68:69], v[118:119], v[68:69]
	v_pk_add_f32 v[66:67], v[224:225], v[66:67]
	v_pk_add_f32 v[68:69], v[116:117], v[68:69]
	v_pk_add_f32 v[66:67], v[222:223], v[66:67]
	v_pk_add_f32 v[68:69], v[114:115], v[68:69]
	v_pk_add_f32 v[66:67], v[220:221], v[66:67]
	v_pk_add_f32 v[68:69], v[112:113], v[68:69]
	v_pk_add_f32 v[66:67], v[218:219], v[66:67]
	v_pk_add_f32 v[68:69], v[110:111], v[68:69]
	v_mfma_f32_32x32x16_bf16 v[18:33], v[70:73], v[74:77], v[18:33]
	v_add_f32_e64 v66, v216, v66
	v_add_f32_e64 v67, v217, v67
	v_add_f32_e64 v68, v108, v68
	v_add_f32_e64 v69, v109, v69
	v_add_f32_e64 v66, v214, v66
	v_add_f32_e64 v67, v215, v67
	v_pk_add_f32 v[68:69], v[106:107], v[68:69]
	v_pk_add_f32 v[66:67], v[90:91], v[66:67]
	v_pk_add_f32 v[68:69], v[104:105], v[68:69]
	v_pk_add_f32 v[66:67], v[88:89], v[66:67]
	v_pk_add_f32 v[68:69], v[102:103], v[68:69]
	v_pk_add_f32 v[66:67], v[86:87], v[66:67]
	v_pk_add_f32 v[68:69], v[100:101], v[68:69]
	v_pk_add_f32 v[66:67], v[84:85], v[66:67]
	v_pk_add_f32 v[68:69], v[98:99], v[68:69]
	v_pk_add_f32 v[66:67], v[82:83], v[66:67]
	v_pk_add_f32 v[68:69], v[68:69], 0 op_sel_hi:[1,0]
	v_lshlrev_b32_e32 v220, 1, v190
	v_pk_add_f32 v[214:215], v[66:67], v[68:69]
	v_lshlrev_b32_e32 v190, 1, v238
	v_readfirstlane_b32 s100, v0
	s_nop 3
	s_lshr_b32 s100, s100, 8
	s_cmp_eq_u32 s100, 0
	s_cbranch_scc1 .Lmla_prio_done
	s_setprio 1
; #define MFMA32(a, b, c) __builtin_amdgcn_mfma_f32_32x32x16_bf16((a), (b), (c), 0, 0, 0)
; DI unsigned pack2(float a, float b) { hwf2_t f = {a, b}; return __builtin_bit_cast(unsigned, __builtin_convertvector(f, hwbf2_t)); }
; template <int DQK>
; DI void attn_item2(char* smem, const bf16_t* __restrict__ Q, const bf16_t* __restrict__ K, const bf16_t* __restrict__ VT,
;                    int qh, int kvh, int b, int q0, bf16_t* __restrict__ Y, int ycol) {
;     ...
; #pragma unroll
;     for (int mt = 0; mt < 2; ++mt) {
; #pragma unroll
;       for (int qn = 0; qn < 2; ++qn) {
;         float rsum = 0;
; #pragma unroll
;         for (int i = 0; i < 16; ++i) { s[qn][mt][i] = __builtin_amdgcn_exp2f(s[qn][mt][i]); rsum += s[qn][mt][i]; }
;         lsum[qn] += rsum;
;       }
; #pragma unroll
;       for (int sx = 0; sx < 2; ++sx) {
;         const int base = mt * 32 + sx * 16 + 4 * h;
;         union { bf16x8 v; uint2 u[2]; } va, vb;
;         va.u[0] = *(const uint2*)(sV + r * VSTR + base);
;         va.u[1] = *(const uint2*)(sV + r * VSTR + base + 8);
;         vb.u[0] = *(const uint2*)(sV + (32 + r) * VSTR + base);
;         vb.u[1] = *(const uint2*)(sV + (32 + r) * VSTR + base + 8);
; #pragma unroll
;         for (int qn = 0; qn < 2; ++qn) {
;           union { bf16x8 v; unsigned u[4]; } pk;
;           pk.u[0] = pack2(s[qn][mt][8 * sx + 0], s[qn][mt][8 * sx + 1]); pk.u[1] = pack2(s[qn][mt][8 * sx + 2], s[qn][mt][8 * sx + 3]);
;           pk.u[2] = pack2(s[qn][mt][8 * sx + 4], s[qn][mt][8 * sx + 5]); pk.u[3] = pack2(s[qn][mt][8 * sx + 6], s[qn][mt][8 * sx + 7]);
;           o[qn][0] = MFMA32(va.v, pk.v, o[qn][0]);
;           o[qn][1] = MFMA32(vb.v, pk.v, o[qn][1]);
;         }
;       }
;     }
.Lmla_prio_done:
	s_branch .LBB0_160
.LBB0_159:
	v_exp_f32_e32 v223, v114
	v_exp_f32_e32 v222, v98
	v_exp_f32_e32 v230, v102
	v_add3_u32 v102, s3, v237, v190
	v_exp_f32_e32 v225, v115
	v_exp_f32_e32 v224, v99
	v_add_u32_e32 v221, 0x3000, v102
	v_add_u32_e32 v238, 0x4000, v102
	v_exp_f32_e32 v227, v116
	v_exp_f32_e32 v226, v100
	v_exp_f32_e32 v228, v101
	v_exp_f32_e32 v232, v103
	v_exp_f32_e32 v234, v104
	ds_read2_b64 v[98:101], v221 offset0:128 offset1:130
	v_exp_f32_e32 v250, v105
	ds_read2_b64 v[102:105], v238 offset0:192 offset1:194
	v_exp_f32_e32 v229, v117
	v_exp_f32_e32 v231, v118
	v_exp_f32_e32 v117, v128
	v_exp_f32_e32 v115, v129
	v_pk_add_f32 v[128:129], v[222:223], 0 op_sel_hi:[1,0]
	v_exp_f32_e32 v233, v119
	v_pk_add_f32 v[128:129], v[224:225], v[128:129]
	v_exp_f32_e32 v235, v120
	v_exp_f32_e32 v251, v121
	v_pk_add_f32 v[128:129], v[226:227], v[128:129]
	v_exp_f32_e32 v193, v122
	v_pk_add_f32 v[128:129], v[228:229], v[128:129]
	v_exp_f32_e32 v192, v106
	v_pk_add_f32 v[128:129], v[230:231], v[128:129]
	v_exp_f32_e32 v219, v123
	v_pk_add_f32 v[128:129], v[232:233], v[128:129]
	v_exp_f32_e32 v217, v124
	v_exp_f32_e32 v123, v125
	v_exp_f32_e32 v121, v126
	v_exp_f32_e32 v119, v127
	v_cvt_pk_bf16_f32 v124, v223, v225
	v_cvt_pk_bf16_f32 v125, v227, v229
	v_cvt_pk_bf16_f32 v126, v231, v233
	v_cvt_pk_bf16_f32 v127, v235, v251
	v_pk_add_f32 v[128:129], v[234:235], v[128:129]
	v_exp_f32_e32 v218, v107
	s_waitcnt lgkmcnt(1)
	v_mfma_f32_32x32x16_bf16 v[34:49], v[98:101], v[124:127], v[34:49]
	v_exp_f32_e32 v216, v108
	v_exp_f32_e32 v122, v109
	v_exp_f32_e32 v120, v110
	v_exp_f32_e32 v118, v111
	v_exp_f32_e32 v116, v112
	v_exp_f32_e32 v114, v113
	v_cvt_pk_bf16_f32 v106, v193, v219
	s_waitcnt lgkmcnt(0)
	v_mfma_f32_32x32x16_bf16 v[50:65], v[102:105], v[124:127], v[50:65]
	v_add_f32_e64 v124, v250, v128
	v_add_f32_e64 v125, v251, v129
	v_cvt_pk_bf16_f32 v126, v230, v232
	v_add_f32_e64 v128, v192, v124
	v_add_f32_e64 v129, v193, v125
	v_cvt_pk_bf16_f32 v124, v222, v224
	v_cvt_pk_bf16_f32 v125, v226, v228
	v_cvt_pk_bf16_f32 v127, v234, v250
	v_cvt_pk_bf16_f32 v110, v192, v218
	v_exp_f32_e32 v225, v86
	v_mfma_f32_32x32x16_bf16 v[2:17], v[98:101], v[124:127], v[2:17]
	ds_read2_b64 v[98:101], v221 offset0:132 offset1:134
	v_cvt_pk_bf16_f32 v107, v217, v123
	v_cvt_pk_bf16_f32 v108, v121, v119
	v_cvt_pk_bf16_f32 v109, v117, v115
	v_exp_f32_e32 v227, v88
	v_exp_f32_e32 v192, v68
	v_exp_f32_e32 v222, v69
	v_mfma_f32_32x32x16_bf16 v[18:33], v[102:105], v[124:127], v[18:33]
	ds_read2_b64 v[102:105], v238 offset0:196 offset1:198
	v_exp_f32_e32 v124, v66
	v_exp_f32_e32 v126, v67
	v_exp_f32_e32 v224, v70
	v_exp_f32_e32 v86, v71
	ds_read2_b64 v[66:69], v221 offset0:136 offset1:138
	v_exp_f32_e32 v226, v72
	v_exp_f32_e32 v88, v73
	ds_read2_b64 v[70:73], v238 offset0:200 offset1:202
	s_waitcnt lgkmcnt(3)
	v_mfma_f32_32x32x16_bf16 v[34:49], v[98:101], v[106:109], v[34:49]
	v_cvt_pk_bf16_f32 v111, v216, v122
	v_cvt_pk_bf16_f32 v112, v120, v118
	v_cvt_pk_bf16_f32 v113, v116, v114
	v_exp_f32_e32 v125, v82
	v_exp_f32_e32 v127, v83
	v_exp_f32_e32 v193, v84
	v_exp_f32_e32 v223, v85
	s_waitcnt lgkmcnt(2)
	v_mfma_f32_32x32x16_bf16 v[50:65], v[102:105], v[106:109], v[50:65]
	v_exp_f32_e32 v87, v87
	v_exp_f32_e32 v89, v89
	v_cvt_pk_bf16_f32 v82, v125, v127
	v_cvt_pk_bf16_f32 v83, v193, v223
	v_cvt_pk_bf16_f32 v84, v225, v87
	v_cvt_pk_bf16_f32 v85, v227, v89
	v_exp_f32_e32 v107, v94
	v_mfma_f32_32x32x16_bf16 v[18:33], v[102:105], v[110:113], v[18:33]
	v_exp_f32_e32 v106, v78
	v_exp_f32_e32 v94, v79
	v_exp_f32_e32 v229, v90
	v_exp_f32_e32 v91, v91
	v_exp_f32_e32 v231, v92
	v_exp_f32_e32 v93, v93
	v_exp_f32_e32 v95, v95
	v_mfma_f32_32x32x16_bf16 v[2:17], v[98:101], v[110:113], v[2:17]
	v_add_f32_e64 v98, v124, 0
	v_add_f32_e64 v99, v125, 0
	v_exp_f32_e32 v109, v96
	v_pk_add_f32 v[98:99], v[126:127], v[98:99]
	v_exp_f32_e32 v97, v97
	v_pk_add_f32 v[98:99], v[192:193], v[98:99]
	v_exp_f32_e32 v228, v74
	v_pk_add_f32 v[98:99], v[222:223], v[98:99]
	s_waitcnt lgkmcnt(1)
	v_mfma_f32_32x32x16_bf16 v[34:49], v[66:69], v[82:85], v[34:49]
	v_add_f32_e64 v98, v224, v98
	v_add_f32_e64 v99, v225, v99
	v_exp_f32_e32 v90, v75
	v_pk_add_f32 v[98:99], v[86:87], v[98:99]
	v_exp_f32_e32 v230, v76
	v_pk_add_f32 v[98:99], v[226:227], v[98:99]
	v_exp_f32_e32 v92, v77
	v_pk_add_f32 v[98:99], v[88:89], v[98:99]
	s_waitcnt lgkmcnt(0)
	v_mfma_f32_32x32x16_bf16 v[50:65], v[70:73], v[82:85], v[50:65]
	v_cvt_pk_bf16_f32 v82, v124, v126
	v_cvt_pk_bf16_f32 v83, v192, v222
	v_cvt_pk_bf16_f32 v84, v224, v86
	v_cvt_pk_bf16_f32 v85, v226, v88
	v_exp_f32_e32 v108, v80
	v_exp_f32_e32 v96, v81
	v_cvt_pk_bf16_f32 v74, v229, v91
	v_mfma_f32_32x32x16_bf16 v[18:33], v[70:73], v[82:85], v[18:33]
	v_add_f32_e64 v70, v218, v128
	v_add_f32_e64 v71, v219, v129
	v_cvt_pk_bf16_f32 v75, v231, v93
	v_add_f32_e64 v78, v216, v70
	v_add_f32_e64 v79, v217, v71
	ds_read2_b64 v[70:73], v238 offset0:204 offset1:206
	v_cvt_pk_bf16_f32 v76, v107, v95
	v_cvt_pk_bf16_f32 v77, v109, v97
	v_pk_add_f32 v[80:81], v[228:229], v[98:99]
	v_mfma_f32_32x32x16_bf16 v[2:17], v[66:69], v[82:85], v[2:17]
	ds_read2_b64 v[66:69], v221 offset0:140 offset1:142
	v_add_f32_e64 v78, v122, v78
	v_add_f32_e64 v79, v123, v79
	s_add_i32 s2, s2, 1
	v_add_f32_e64 v78, v120, v78
	v_add_f32_e64 v79, v121, v79
	s_cmpk_lg_i32 s2, 0x85
	v_pk_add_f32 v[78:79], v[118:119], v[78:79]
	s_waitcnt lgkmcnt(0)
	v_mfma_f32_32x32x16_bf16 v[34:49], v[66:69], v[74:77], v[34:49]
	v_add_f32_e64 v78, v116, v78
	v_add_f32_e64 v79, v117, v79
	v_add_f32_e64 v78, v114, v78
	v_add_f32_e64 v79, v115, v79
	v_add_f32_e64 v78, v214, v78
	v_add_f32_e64 v79, v215, v79
	v_mfma_f32_32x32x16_bf16 v[50:65], v[70:73], v[74:77], v[50:65]
	v_add_f32_e64 v74, v90, v80
	v_add_f32_e64 v75, v91, v81
	v_cvt_pk_bf16_f32 v76, v106, v94
	v_add_f32_e64 v74, v230, v74
	v_add_f32_e64 v75, v231, v75
	v_cvt_pk_bf16_f32 v77, v108, v96
	v_pk_add_f32 v[80:81], v[92:93], v[74:75]
	v_cvt_pk_bf16_f32 v74, v228, v90
	v_cvt_pk_bf16_f32 v75, v230, v92
	s_nop 1
	v_mfma_f32_32x32x16_bf16 v[2:17], v[66:69], v[74:77], v[2:17]
	v_add_f32_e64 v66, v106, v80
	v_add_f32_e64 v67, v107, v81
	v_add_f32_e64 v66, v94, v66
	v_add_f32_e64 v67, v95, v67
	v_add_f32_e64 v66, v108, v66
	v_add_f32_e64 v67, v109, v67
	v_pk_add_f32 v[66:67], v[96:97], v[66:67]
	v_mfma_f32_32x32x16_bf16 v[18:33], v[70:73], v[74:77], v[18:33]
	v_add_f32_e64 v214, v66, v78
	v_add_f32_e64 v215, v67, v79
	s_cbranch_scc0 .LBB0_141

; __global__ void __launch_bounds__(512, 2) mega(Params p, int ph_lo, int ph_hi) {
	.amdhsa_kernel _Z4mega6Paramsii
		.amdhsa_group_segment_fixed_size 0
		.amdhsa_private_segment_fixed_size 0
		.amdhsa_kernarg_size 792
		.amdhsa_user_sgpr_count 2
		.amdhsa_user_sgpr_dispatch_ptr 0
		.amdhsa_user_sgpr_queue_ptr 0
		.amdhsa_user_sgpr_kernarg_segment_ptr 1
		.amdhsa_user_sgpr_dispatch_id 0
		.amdhsa_user_sgpr_kernarg_preload_length 0
		.amdhsa_user_sgpr_kernarg_preload_offset 0
		.amdhsa_user_sgpr_private_segment_size 0
		.amdhsa_uses_dynamic_stack 0
		.amdhsa_enable_private_segment 0
		.amdhsa_system_sgpr_workgroup_id_x 1
		.amdhsa_system_sgpr_workgroup_id_y 0
		.amdhsa_system_sgpr_workgroup_id_z 0
		.amdhsa_system_sgpr_workgroup_info 0
		.amdhsa_system_vgpr_workitem_id 0
		.amdhsa_next_free_vgpr 256
		.amdhsa_next_free_sgpr 102
		.amdhsa_accum_offset 256
		.amdhsa_reserve_vcc 1
		.amdhsa_float_round_mode_32 0
		.amdhsa_float_round_mode_16_64 0
		.amdhsa_float_denorm_mode_32 3
		.amdhsa_float_denorm_mode_16_64 3
		.amdhsa_dx10_clamp 1
		.amdhsa_ieee_mode 1
		.amdhsa_fp16_overflow 0
		.amdhsa_tg_split 0
		.amdhsa_exception_fp_ieee_invalid_op 0
		.amdhsa_exception_fp_denorm_src 0
		.amdhsa_exception_fp_ieee_div_zero 0
		.amdhsa_exception_fp_ieee_overflow 0
		.amdhsa_exception_fp_ieee_underflow 0
		.amdhsa_exception_fp_ieee_inexact 0
		.amdhsa_exception_int_div_zero 0
	.end_amdhsa_kernel

; __global__ void __launch_bounds__(512, 2) mega(Params p, int ph_lo, int ph_hi) {
amdhsa.kernels:
  - .agpr_count:     0
    .args:
      - .offset:         0
        .size:           528
        .value_kind:     by_value
      - .offset:         528
        .size:           4
        .value_kind:     by_value
      - .offset:         532
        .size:           4
        .value_kind:     by_value
      - .offset:         536
        .size:           4
        .value_kind:     hidden_block_count_x
      - .offset:         540
        .size:           4
        .value_kind:     hidden_block_count_y
      - .offset:         544
        .size:           4
        .value_kind:     hidden_block_count_z
      - .offset:         548
        .size:           2
        .value_kind:     hidden_group_size_x
      - .offset:         550
        .size:           2
        .value_kind:     hidden_group_size_y
      - .offset:         552
        .size:           2
        .value_kind:     hidden_group_size_z
      - .offset:         554
        .size:           2
        .value_kind:     hidden_remainder_x
      - .offset:         556
        .size:           2
        .value_kind:     hidden_remainder_y
      - .offset:         558
        .size:           2
        .value_kind:     hidden_remainder_z
      - .offset:         576
        .size:           8
        .value_kind:     hidden_global_offset_x
      - .offset:         584
        .size:           8
        .value_kind:     hidden_global_offset_y
      - .offset:         592
        .size:           8
        .value_kind:     hidden_global_offset_z
      - .offset:         600
        .size:           2
        .value_kind:     hidden_grid_dims
      - .offset:         656
        .size:           4
        .value_kind:     hidden_dynamic_lds_size
    .group_segment_fixed_size: 0
    .kernarg_segment_align: 8
    .kernarg_segment_size: 792
    .language:       OpenCL C
    .language_version:
      - 2
      - 0
    .max_flat_workgroup_size: 512
    .name:           _Z4mega6Paramsii
    .private_segment_fixed_size: 0
    .sgpr_count:     108
    .sgpr_spill_count: 273
    .symbol:         _Z4mega6Paramsii.kd
    .uniform_work_group_size: 1
    .uses_dynamic_stack: false
    .vgpr_count:     256
    .vgpr_spill_count: 0
    .wavefront_size: 64
